# A7 norm loop: gain vectors register-resident (counted waits between row loads adjusted)
# speedup vs baseline: 1.0074x; 1.0074x over previous
; template <bool XOUT_BF, int NR>
; DI void norm_rows(const bf16_t* xin, const bf16_t* Rb, const float* gpost, void* xout, const float* gpre, bf16_t* xnb, size_t row0, size_t rstride, int lane) {
;     f32x4 v[NR][4], r[NR][4];
; #pragma unroll
;     for (int q = 0; q < NR; ++q)
; #pragma unroll
;         for (int j = 0; j < 4; ++j) { const size_t off = (row0 + q * rstride) * D + 4 * lane + 256 * j;
; __global__ void __launch_bounds__(512, 2) mega(Args args) {
;     ...
;             PH_BEGIN
;                 for (int m = gw; m < HT; m += 4 * NGW) norm_rows<true, 4>(XB, R, in.g_mix_post + l * D, XB, in.g_x_pre + l * D, XN, (size_t)half * HT + m, (size_t)NGW, lane);
.LBB0_983:
	v_readlane_b32 s4, v255, 1
	v_readlane_b32 s5, v255, 2
	s_cmp_ge_i32 s26, s4
	s_cselect_b64 s[4:5], -1, 0
	s_and_b64 s[2:3], s[4:5], s[2:3]
	s_andn2_b64 vcc, exec, s[2:3]
	s_cbranch_vccnz .LBB0_994
	s_mov_b64 s[16:17], s[62:63]
	s_load_dwordx4 s[4:7], s[16:17], 0x10
	s_load_dwordx2 s[14:15], s[16:17], 0xa8
	s_load_dwordx4 s[8:11], s[16:17], 0xe8
	s_mov_b32 s3, s81
	v_readlane_b32 s2, v255, 0
	s_mov_b32 s12, s83
	v_readlane_b32 s13, v255, 3
	s_lshl_b32 s2, s2, 3
	s_add_i32 s2, s2, s13
	v_lshl_add_u32 v0, s13, 6, v249
	s_lshl_b32 s12, s3, 3
	v_and_b32_e32 v64, 63, v0
	s_cmpk_gt_i32 s2, 0x3fff
	v_lshlrev_b32_e32 v4, 4, v64
	s_cbranch_scc1 .LBB0_989
	s_load_dwordx2 s[20:21], s[16:17], 0x28
	s_load_dwordx2 s[22:23], s[16:17], 0x98
	s_waitcnt lgkmcnt(0)
	s_add_u32 s16, s10, 0x3d00000
	s_addc_u32 s17, s11, 0
	v_readlane_b32 s24, v255, 15
	s_add_u32 s18, s10, 0x7d00000
	v_readlane_b32 s25, v255, 16
	s_addc_u32 s19, s11, 0
	s_lshl_b64 s[24:25], s[24:25], 2
	s_add_u32 s20, s20, s24
	v_readlane_b32 s28, v255, 19
	s_addc_u32 s21, s21, s25
	s_lshl_b32 s33, s28, 14
	s_ashr_i32 s13, s12, 31
	v_mov_b32_e32 v5, v177
	s_cmp_lg_u64 s[8:9], 0
	v_lshl_add_u64 v[6:7], s[20:21], 0, v[4:5]
	s_cselect_b64 s[20:21], -1, 0
	s_add_u32 s22, s22, s24
	s_addc_u32 s23, s23, s25
	v_readlane_b32 s29, v255, 20
	v_lshl_add_u64 v[8:9], s[22:23], 0, v[4:5]
	global_load_dwordx4 v[140:143], v[6:7], off
	global_load_dwordx4 v[144:147], v[6:7], off offset:1024
	global_load_dwordx4 v[148:151], v[6:7], off offset:2048
	global_load_dwordx4 v[152:155], v[6:7], off offset:3072
	global_load_dwordx4 v[156:159], v[8:9], off
	global_load_dwordx4 v[160:163], v[8:9], off offset:1024
	global_load_dwordx4 v[164:167], v[8:9], off offset:2048
	global_load_dwordx4 v[168:171], v[8:9], off offset:3072
	s_lshl_b32 s22, s3, 5
	s_ashr_i32 s3, s2, 31
	s_mov_b32 s29, s45
	s_ashr_i32 s23, s22, 31
	s_lshl_b64 s[26:27], s[2:3], 11
	s_lshl_b64 s[56:57], s[28:29], 25
	s_lshl_b64 s[24:25], s[22:23], 11
	s_add_u32 s23, s26, s56
	s_addc_u32 s26, s27, s57
	v_mov_b32_e32 v11, s26
	s_add_u32 s26, s10, 0x3d00200
	s_addc_u32 s27, s11, 0
	s_add_u32 s28, s10, 0x3d00400
	s_addc_u32 s29, s11, 0
	s_add_u32 s30, s10, 0x3d00600
	s_addc_u32 s31, s11, 0
	v_lshlrev_b32_e32 v0, 3, v0
	s_add_u32 s34, s10, 0x7d00200
	v_and_b32_e32 v176, 0x1f8, v0
	s_addc_u32 s35, s11, 0
	s_lshl_b64 s[36:37], s[12:13], 1
	v_or_b32_e32 v10, s23, v176
	s_add_u32 s23, s33, s36
	s_addc_u32 s37, 0, s37
	s_add_u32 s36, s23, s2
	s_addc_u32 s37, s37, s3
	s_lshl_b64 s[48:49], s[36:37], 11
	s_add_u32 s36, s10, s48
	s_addc_u32 s37, s11, s49
	s_add_u32 s38, s10, 0x7d00400
	s_addc_u32 s39, s11, 0
	s_lshl_b64 s[40:41], s[12:13], 12
	s_add_u32 s40, s26, s40
	s_addc_u32 s41, s27, s41
	s_add_u32 s46, s10, 0x7d00600
	s_addc_u32 s47, s11, 0
	s_add_u32 s48, s8, s48
	s_addc_u32 s49, s9, s49
	s_mul_i32 s42, s12, 3
	s_mul_hi_i32 s23, s12, 3
	s_add_u32 s42, s33, s42
	s_addc_u32 s23, 0, s23
	s_add_u32 s50, s42, s2
	s_addc_u32 s51, s23, s3
	s_lshl_b64 s[58:59], s[50:51], 11
	s_add_u32 s50, s10, s58
	s_addc_u32 s51, s11, s59
	s_mul_i32 s42, s12, 0x1800
	s_mul_hi_i32 s23, s12, 0x1800
	s_add_u32 s52, s26, s42
	s_addc_u32 s53, s27, s23
	s_add_u32 s60, s12, s2
	s_addc_u32 s61, s13, s3
	s_lshl_b64 s[54:55], s[60:61], 11
	s_add_u32 s54, s54, 0x3d00200
	s_addc_u32 s55, s55, 0
	s_add_u32 s56, s10, s56
	s_addc_u32 s57, s11, s57
	v_lshl_add_u64 v[12:13], s[56:57], 0, v[176:177]
	s_add_u32 s56, s8, s58
	s_addc_u32 s57, s9, s59
	s_add_u32 s58, s60, s33
	s_addc_u32 s59, s61, 0
	s_lshl_b64 s[58:59], s[58:59], 11
	s_add_u32 s10, s10, s58
	s_addc_u32 s11, s11, s59
	s_add_u32 s58, s8, s58
	s_addc_u32 s59, s9, s59
	s_mov_b64 s[60:61], s[8:9]
	s_mov_b32 s3, s2
	s_branch .LBB0_987

; DI float bflo(unsigned w) { return __uint_as_float(w << 16); }
; DI float bfhi(unsigned w) { return __uint_as_float(w & 0xffff0000u); }
; template <bool XOUT_BF, int NR>
; DI void norm_rows(const bf16_t* xin, const bf16_t* Rb, const float* gpost, void* xout, const float* gpre, bf16_t* xnb, size_t row0, size_t rstride, int lane) {
;     f32x4 v[NR][4], r[NR][4];
; #pragma unroll
;     for (int q = 0; q < NR; ++q)
; #pragma unroll
;         for (int j = 0; j < 4; ++j) { const size_t off = (row0 + q * rstride) * D + 4 * lane + 256 * j;
;             const u32x2 w = __builtin_nontemporal_load((const u32x2*)(xin + off)); v[q][j] = (f32x4){bflo(w.x), bfhi(w.x), bflo(w.y), bfhi(w.y)};
;             const u32x2 w2 = __builtin_nontemporal_load((const u32x2*)(Rb + off)); r[q][j] = (f32x4){bflo(w2.x), bfhi(w2.x), bflo(w2.y), bfhi(w2.y)}; }
;     float ss[NR], s2[NR];
; #pragma unroll
;     for (int q = 0; q < NR; ++q) { ss[q] = 0.f; s2[q] = 0.f;
; #pragma unroll
;         for (int j = 0; j < 4; ++j) ss[q] += (r[q][j][0] * r[q][j][0] + r[q][j][1] * r[q][j][1]) + (r[q][j][2] * r[q][j][2] + r[q][j][3] * r[q][j][3]); }
; #pragma unroll
;     for (int o = 1; o < 64; o <<= 1)
; #pragma unroll
;         for (int q = 0; q < NR; ++q) ss[q] += __shfl_xor(ss[q], o);
.LBB0_987:
	s_waitcnt vmcnt(16)
	v_lshl_add_u64 v[0:1], s[46:47], 0, v[10:11]
	global_load_dwordx2 v[26:27], v[0:1], off nt
	v_lshl_add_u64 v[0:1], s[18:19], 0, v[10:11]
	global_load_dwordx2 v[24:25], v[0:1], off nt
	v_lshl_add_u64 v[0:1], s[34:35], 0, v[10:11]
	global_load_dwordx2 v[22:23], v[0:1], off nt
	v_lshl_add_u64 v[0:1], s[38:39], 0, v[10:11]
	global_load_dwordx2 v[20:21], v[0:1], off nt
	v_lshl_add_u64 v[16:17], s[16:17], 0, v[10:11]
	v_lshl_add_u64 v[14:15], s[26:27], 0, v[10:11]
	global_load_dwordx2 v[38:39], v[16:17], off nt
	global_load_dwordx2 v[66:67], v[14:15], off nt
	v_lshl_add_u64 v[28:29], s[10:11], 0, v[176:177]
	s_mov_b32 s13, 0x3d00000
	v_add_co_u32_e32 v54, vcc, s13, v28
	s_mov_b32 s23, 0x7d00000
	s_nop 0
	v_addc_co_u32_e32 v55, vcc, 0, v29, vcc
	v_add_co_u32_e32 v28, vcc, s23, v28
	v_lshl_add_u64 v[30:31], v[12:13], 0, s[54:55]
	s_nop 0
	v_addc_co_u32_e32 v29, vcc, 0, v29, vcc
	s_brev_b32 s33, 32
	v_add_co_u32_e32 v30, vcc, s33, v30
	v_lshl_add_u64 v[32:33], s[36:37], 0, v[176:177]
	s_nop 0
	v_addc_co_u32_e32 v31, vcc, 0, v31, vcc
	v_add_co_u32_e32 v34, vcc, s13, v32
	v_lshl_add_u64 v[18:19], s[40:41], 0, v[10:11]
	s_nop 0
	v_addc_co_u32_e32 v35, vcc, 0, v33, vcc
	v_add_co_u32_e32 v32, vcc, s23, v32
	v_lshl_add_u64 v[36:37], s[50:51], 0, v[176:177]
	s_nop 0
	v_addc_co_u32_e32 v33, vcc, 0, v33, vcc
	v_add_co_u32_e32 v40, vcc, s33, v18
	global_load_dwordx2 v[82:83], v[28:29], off nt
	s_nop 0
	v_addc_co_u32_e32 v41, vcc, 0, v19, vcc
	v_lshl_add_u64 v[44:45], s[52:53], 0, v[10:11]
	s_waitcnt vmcnt(0)
	v_mov_b32_e32 v0, v140
	v_mov_b32_e32 v1, v141
	v_mov_b32_e32 v2, v142
	v_mov_b32_e32 v3, v143
	v_lshlrev_b32_e32 v69, 16, v26
	v_lshlrev_b32_e32 v72, 16, v27
	v_and_b32_e32 v73, 0xffff0000, v27
	v_and_b32_e32 v27, 0xffff0000, v24
	v_and_b32_e32 v51, 0xffff0000, v25
	v_and_b32_e32 v71, 0xffff0000, v26
	v_lshlrev_b32_e32 v26, 16, v24
	v_lshlrev_b32_e32 v50, 16, v25
	v_and_b32_e32 v77, 0xffff0000, v23
	v_and_b32_e32 v76, 0xffff0000, v22
	v_lshlrev_b32_e32 v78, 16, v20
	v_and_b32_e32 v79, 0xffff0000, v20
	v_lshlrev_b32_e32 v80, 16, v21
	v_and_b32_e32 v81, 0xffff0000, v21
	v_mul_f32_e32 v20, v51, v51
	v_mul_f32_e32 v24, v27, v27
	v_mov_b32_e32 v21, v69
	v_lshlrev_b32_e32 v75, 16, v23
	v_lshlrev_b32_e32 v74, 16, v22
	v_pk_mul_f32 v[22:23], v[76:77], v[76:77]
	v_pk_fma_f32 v[48:49], v[50:51], v[50:51], v[20:21] op_sel_hi:[1,1,0]
	v_pk_fma_f32 v[24:25], v[26:27], v[26:27], v[24:25] op_sel_hi:[1,1,0]
	v_mul_f32_e32 v42, v79, v79
	v_mul_f32_e32 v46, v81, v81
	v_pk_fma_f32 v[22:23], v[74:75], v[74:75], v[22:23]
	v_mov_b32_e32 v68, v24
	v_mov_b32_e32 v20, v48
	v_mul_f32_e32 v5, v71, v71
	v_mul_f32_e32 v52, v72, v72
	v_mul_f32_e32 v53, v73, v73
	v_pk_fma_f32 v[42:43], v[78:79], v[78:79], v[42:43] op_sel_hi:[1,1,0]
	v_pk_fma_f32 v[46:47], v[80:81], v[80:81], v[46:47] op_sel_hi:[1,1,0]
	v_pk_add_f32 v[24:25], v[24:25], v[48:49]
	v_pk_add_f32 v[22:23], v[22:23], v[22:23] op_sel:[0,1] op_sel_hi:[1,0]
	v_pk_mul_f32 v[20:21], v[68:69], v[20:21]
	v_mov_b32_e32 v43, v52
	v_mov_b32_e32 v47, v53
	v_mov_b32_e32 v23, v5
	v_mov_b32_e32 v25, v21
	v_pk_add_f32 v[42:43], v[42:43], v[46:47]
	v_pk_add_f32 v[20:21], v[24:25], v[22:23]
	v_mov_b32_e32 v96, v74
	v_pk_add_f32 v[20:21], v[20:21], v[42:43]
	v_add_co_u32_e32 v42, vcc, s13, v36
	v_add_f32_e32 v5, v20, v21
	ds_bpermute_b32 v20, v206, v5
	v_addc_co_u32_e32 v43, vcc, 0, v37, vcc
	v_add_co_u32_e32 v22, vcc, s23, v36
	s_waitcnt lgkmcnt(0)
	v_add_f32_e32 v5, v5, v20
	ds_bpermute_b32 v20, v207, v5
	v_addc_co_u32_e32 v23, vcc, 0, v37, vcc
	v_mov_b32_e32 v97, v76
	v_mov_b32_e32 v76, v75
	s_waitcnt lgkmcnt(0)
	v_add_f32_e32 v5, v5, v20
	ds_bpermute_b32 v24, v208, v5
	global_load_dwordx2 v[84:85], v[54:55], off nt
	global_load_dwordx2 v[86:87], v[54:55], off offset:512 nt
	global_load_dwordx2 v[20:21], v[54:55], off offset:1024 nt
	global_load_dwordx2 v[28:29], v[54:55], off offset:1536 nt
	v_mov_b32_e32 v70, v69
	s_waitcnt lgkmcnt(0)
	v_add_f32_e32 v5, v5, v24
	ds_bpermute_b32 v36, v209, v5
	global_load_dwordx2 v[88:89], v[30:31], off nt
	global_load_dwordx2 v[90:91], v[30:31], off offset:512 nt
	global_load_dwordx2 v[92:93], v[30:31], off offset:1024 nt
	global_load_dwordx2 v[24:25], v[34:35], off nt
	global_load_dwordx2 v[58:59], v[32:33], off nt
	global_load_dwordx2 v[56:57], v[40:41], off offset:512 nt
	global_load_dwordx2 v[60:61], v[40:41], off offset:1024 nt
	s_nop 0
	global_load_dwordx2 v[32:33], v[42:43], off nt
	global_load_dwordx2 v[46:47], v[22:23], off nt
	v_lshlrev_b32_e32 v22, 16, v38
	v_and_b32_e32 v23, 0xffff0000, v38
	s_waitcnt lgkmcnt(0)
	v_add_f32_e32 v5, v5, v36
	ds_bpermute_b32 v30, v210, v5
	v_and_b32_e32 v31, 0xffff0000, v39
	v_add_co_u32_e32 v38, vcc, s33, v44
	s_waitcnt lgkmcnt(0)
	v_add_f32_e32 v5, v5, v30
	ds_bpermute_b32 v36, v211, v5
	v_lshlrev_b32_e32 v30, 16, v39
	v_addc_co_u32_e32 v39, vcc, 0, v45, vcc
	s_andn2_b64 vcc, exec, s[20:21]
	s_waitcnt lgkmcnt(0)
; DI unsigned cvt_pk_bf16(float lo, float hi) { const f32x2 v = {lo, hi}; return __builtin_bit_cast(unsigned, __builtin_convertvector(v, bf16x2_t)); }
; DI float bflo(unsigned w) { return __uint_as_float(w << 16); }
; DI float bfhi(unsigned w) { return __uint_as_float(w & 0xffff0000u); }
; template <bool XOUT_BF, int NR>
; DI void norm_rows(const bf16_t* xin, const bf16_t* Rb, const float* gpost, void* xout, const float* gpre, bf16_t* xnb, size_t row0, size_t rstride, int lane) {
;     ...
;     for (int q = 0; q < NR; ++q) { const float rinv = __builtin_amdgcn_rsqf(ss[q] * (1.f / 1024.f) + EPS);
; #pragma unroll
;         for (int j = 0; j < 4; ++j) { const size_t off = (row0 + q * rstride) * D + 4 * lane + 256 * j;
;             const f32x4 g = *(const f32x4*)(gpost + 4 * lane + 256 * j); v[q][j] += r[q][j] * rinv * g;
;             if (XOUT_BF) { u32x2 w; w.x = cvt_pk_bf16(v[q][j][0], v[q][j][1]); w.y = cvt_pk_bf16(v[q][j][2], v[q][j][3]); __builtin_nontemporal_store(w, (u32x2*)((bf16_t*)xout + off));
;                            v[q][j] = (f32x4){bflo(w.x), bfhi(w.x), bflo(w.y), bfhi(w.y)}; }
;             else *(f32x4*)((float*)xout + off) = v[q][j];
;             s2[q] += (v[q][j][0] * v[q][j][0] + v[q][j][1] * v[q][j][1]) + (v[q][j][2] * v[q][j][2] + v[q][j][3] * v[q][j][3]); } }
;     if (xnb) {
; #pragma unroll
;         for (int o = 1; o < 64; o <<= 1)
; #pragma unroll
;             for (int q = 0; q < NR; ++q) s2[q] += __shfl_xor(s2[q], o);
	v_add_f32_e32 v5, v5, v36
	v_fmamk_f32 v5, v5, 0x3a800000, v217
	v_rsq_f32_e32 v68, v5
	global_load_dwordx2 v[48:49], v[38:39], off offset:512 nt
	global_load_dwordx2 v[36:37], v[38:39], off offset:1024 nt
	v_pk_mul_f32 v[26:27], v[68:69], v[26:27] op_sel_hi:[0,1]
	v_pk_mul_f32 v[50:51], v[68:69], v[50:51] op_sel_hi:[0,1]
	v_pk_fma_f32 v[2:3], v[2:3], v[50:51], v[30:31]
	v_pk_fma_f32 v[0:1], v[0:1], v[26:27], v[22:23]
	v_cvt_pk_bf16_f32 v23, v2, v3
	v_cvt_pk_bf16_f32 v22, v0, v1
	global_load_dwordx2 v[62:63], v[40:41], off nt
	global_load_dwordx2 v[30:31], v[18:19], off offset:512 nt
	global_load_dwordx2 v[52:53], v[18:19], off offset:1024 nt
	global_load_dwordx2 v[26:27], v[18:19], off nt
	global_load_dwordx2 v[50:51], v[38:39], off nt
	s_nop 0
	global_load_dwordx2 v[38:39], v[44:45], off offset:512 nt
	global_load_dwordx2 v[40:41], v[44:45], off offset:1024 nt
	s_nop 0
	global_load_dwordx2 v[44:45], v[44:45], off nt
	v_pk_mul_f32 v[74:75], v[68:69], v[96:97] op_sel_hi:[0,1]
	global_store_dwordx2 v[16:17], v[22:23], off nt
	v_lshlrev_b32_e32 v16, 16, v66
	v_and_b32_e32 v17, 0xffff0000, v66
	v_lshlrev_b32_e32 v66, 16, v67
	v_and_b32_e32 v67, 0xffff0000, v67
	v_pk_mul_f32 v[76:77], v[68:69], v[76:77] op_sel_hi:[0,1]
	v_lshl_add_u64 v[18:19], s[28:29], 0, v[10:11]
	global_load_dwordx2 v[94:95], v[18:19], off nt
	v_pk_mul_f32 v[78:79], v[68:69], v[78:79] op_sel_hi:[0,1]
	v_pk_mul_f32 v[80:81], v[68:69], v[80:81] op_sel_hi:[0,1]
	v_pk_mul_f32 v[70:71], v[68:69], v[70:71] op_sel_hi:[0,1]
	v_pk_mul_f32 v[68:69], v[68:69], v[72:73] op_sel_hi:[0,1]
	s_waitcnt vmcnt(20)
	v_mov_b32_e32 v0, v144
	v_mov_b32_e32 v1, v145
	v_mov_b32_e32 v2, v146
	v_mov_b32_e32 v3, v147
	v_and_b32_e32 v73, 0xffff0000, v89
	v_and_b32_e32 v72, 0xffff0000, v88
	s_waitcnt vmcnt(1)
	v_pk_fma_f32 v[2:3], v[2:3], v[76:77], v[66:67]
	v_pk_fma_f32 v[0:1], v[0:1], v[74:75], v[16:17]
	v_lshl_add_u64 v[66:67], s[30:31], 0, v[10:11]
	v_cvt_pk_bf16_f32 v0, v0, v1
	v_cvt_pk_bf16_f32 v1, v2, v3
	global_store_dwordx2 v[14:15], v[0:1], off nt
	s_waitcnt vmcnt(1)
	v_mov_b32_e32 v14, v148
	v_mov_b32_e32 v15, v149
	v_mov_b32_e32 v16, v150
	v_mov_b32_e32 v17, v151
	v_lshlrev_b32_e32 v2, 16, v94
	v_and_b32_e32 v3, 0xffff0000, v94
	v_lshlrev_b32_e32 v76, 16, v95
	v_and_b32_e32 v77, 0xffff0000, v95
	global_load_dwordx2 v[74:75], v[66:67], off nt
	s_waitcnt vmcnt(0)
	v_pk_fma_f32 v[16:17], v[16:17], v[80:81], v[76:77]
	v_pk_fma_f32 v[2:3], v[14:15], v[78:79], v[2:3]
	v_lshlrev_b32_e32 v77, 16, v92
	v_cvt_pk_bf16_f32 v2, v2, v3
	v_cvt_pk_bf16_f32 v3, v16, v17
	global_store_dwordx2 v[18:19], v[2:3], off nt
	s_nop 0
	v_mov_b32_e32 v14, v152
	v_mov_b32_e32 v15, v153
	v_mov_b32_e32 v16, v154
	v_mov_b32_e32 v17, v155
	v_lshlrev_b32_e32 v18, 16, v74
	v_and_b32_e32 v19, 0xffff0000, v74
	v_lshlrev_b32_e32 v74, 16, v75
	v_and_b32_e32 v75, 0xffff0000, v75
	v_and_b32_e32 v79, 0xffff0000, v92
	v_lshlrev_b32_e32 v80, 16, v93
	v_and_b32_e32 v81, 0xffff0000, v93
	v_lshlrev_b32_e32 v92, 16, v82
	v_and_b32_e32 v93, 0xffff0000, v82
	v_lshlrev_b32_e32 v82, 16, v83
	v_and_b32_e32 v83, 0xffff0000, v83
	v_mul_f32_e32 v76, v93, v93
	v_pk_fma_f32 v[96:97], v[92:93], v[92:93], v[76:77] op_sel_hi:[1,1,0]
	v_mul_f32_e32 v5, v79, v79
	v_mov_b32_e32 v76, v96
	v_mul_f32_e32 v65, v80, v80
	v_mul_f32_e32 v100, v81, v81
	s_nop 0
	v_pk_fma_f32 v[16:17], v[68:69], v[16:17], v[74:75]
	v_pk_fma_f32 v[14:15], v[70:71], v[14:15], v[18:19]
	v_cvt_pk_bf16_f32 v19, v16, v17
	v_cvt_pk_bf16_f32 v18, v14, v15
	global_store_dwordx2 v[66:67], v[18:19], off nt
	v_mul_f32_e32 v66, v83, v83
	v_mov_b32_e32 v67, v77
	v_lshlrev_b32_e32 v71, 16, v89
	v_lshlrev_b32_e32 v70, 16, v88
	v_and_b32_e32 v75, 0xffff0000, v90
	v_and_b32_e32 v89, 0xffff0000, v91
	v_pk_mul_f32 v[68:69], v[72:73], v[72:73]
	v_pk_fma_f32 v[94:95], v[82:83], v[82:83], v[66:67] op_sel_hi:[1,1,0]
	v_lshlrev_b32_e32 v74, 16, v90
	v_lshlrev_b32_e32 v88, 16, v91
	v_mul_f32_e32 v78, v75, v75
	v_mul_f32_e32 v90, v89, v89
	v_pk_fma_f32 v[68:69], v[70:71], v[70:71], v[68:69]
	v_mov_b32_e32 v66, v94
	v_pk_fma_f32 v[98:99], v[74:75], v[74:75], v[78:79] op_sel_hi:[1,1,0]
	v_pk_fma_f32 v[90:91], v[88:89], v[88:89], v[90:91] op_sel_hi:[1,1,0]
	v_pk_add_f32 v[94:95], v[96:97], v[94:95]
	v_pk_add_f32 v[68:69], v[68:69], v[68:69] op_sel:[0,1] op_sel_hi:[1,0]
	v_pk_mul_f32 v[66:67], v[76:77], v[66:67]
	v_mov_b32_e32 v99, v65
	v_mov_b32_e32 v91, v100
	v_mov_b32_e32 v69, v5
	v_mov_b32_e32 v95, v67
	v_pk_add_f32 v[90:91], v[98:99], v[90:91]
	v_pk_add_f32 v[66:67], v[94:95], v[68:69]
	v_lshlrev_b32_e32 v68, 16, v85
	v_pk_add_f32 v[66:67], v[66:67], v[90:91]
	v_and_b32_e32 v69, 0xffff0000, v85
	v_add_f32_e32 v5, v66, v67
	ds_bpermute_b32 v65, v206, v5
	v_lshlrev_b32_e32 v66, 16, v84
	v_and_b32_e32 v67, 0xffff0000, v84
	v_mov_b32_e32 v78, v77
	s_waitcnt lgkmcnt(0)
	v_add_f32_e32 v5, v5, v65
	ds_bpermute_b32 v65, v207, v5
	s_waitcnt lgkmcnt(0)
	v_add_f32_e32 v5, v5, v65
	ds_bpermute_b32 v65, v208, v5
	s_waitcnt lgkmcnt(0)
	v_add_f32_e32 v5, v5, v65
	ds_bpermute_b32 v65, v209, v5
	s_waitcnt lgkmcnt(0)
	v_add_f32_e32 v5, v5, v65
	ds_bpermute_b32 v65, v210, v5
	s_waitcnt lgkmcnt(0)
	v_add_f32_e32 v5, v5, v65
	ds_bpermute_b32 v65, v211, v5
	s_waitcnt lgkmcnt(0)
; DI unsigned cvt_pk_bf16(float lo, float hi) { const f32x2 v = {lo, hi}; return __builtin_bit_cast(unsigned, __builtin_convertvector(v, bf16x2_t)); }
; DI float bflo(unsigned w) { return __uint_as_float(w << 16); }
; DI float bfhi(unsigned w) { return __uint_as_float(w & 0xffff0000u); }
; template <bool XOUT_BF, int NR>
; DI void norm_rows(const bf16_t* xin, const bf16_t* Rb, const float* gpost, void* xout, const float* gpre, bf16_t* xnb, size_t row0, size_t rstride, int lane) {
;     ...
;     for (int q = 0; q < NR; ++q) { const float rinv = __builtin_amdgcn_rsqf(ss[q] * (1.f / 1024.f) + EPS);
; #pragma unroll
;         for (int j = 0; j < 4; ++j) { const size_t off = (row0 + q * rstride) * D + 4 * lane + 256 * j;
;             const f32x4 g = *(const f32x4*)(gpost + 4 * lane + 256 * j); v[q][j] += r[q][j] * rinv * g;
;             if (XOUT_BF) { u32x2 w; w.x = cvt_pk_bf16(v[q][j][0], v[q][j][1]); w.y = cvt_pk_bf16(v[q][j][2], v[q][j][3]); __builtin_nontemporal_store(w, (u32x2*)((bf16_t*)xout + off));
;                            v[q][j] = (f32x4){bflo(w.x), bfhi(w.x), bflo(w.y), bfhi(w.y)}; }
;             else *(f32x4*)((float*)xout + off) = v[q][j];
;             s2[q] += (v[q][j][0] * v[q][j][0] + v[q][j][1] * v[q][j][1]) + (v[q][j][2] * v[q][j][2] + v[q][j][3] * v[q][j][3]); } }
;     if (xnb) {
; #pragma unroll
;         for (int o = 1; o < 64; o <<= 1)
; #pragma unroll
;             for (int q = 0; q < NR; ++q) s2[q] += __shfl_xor(s2[q], o);
	v_add_f32_e32 v5, v5, v65
	v_fmamk_f32 v5, v5, 0x3a800000, v217
	v_rsq_f32_e32 v76, v5
	s_nop 0
	v_pk_mul_f32 v[84:85], v[76:77], v[92:93] op_sel_hi:[0,1]
	v_pk_mul_f32 v[82:83], v[76:77], v[82:83] op_sel_hi:[0,1]
	v_pk_mul_f32 v[78:79], v[76:77], v[78:79] op_sel_hi:[0,1]
	s_nop 0
	v_mov_b32_e32 v14, v140
	v_mov_b32_e32 v15, v141
	v_mov_b32_e32 v16, v142
	v_mov_b32_e32 v17, v143
	v_pk_fma_f32 v[16:17], v[82:83], v[16:17], v[68:69]
	v_pk_fma_f32 v[14:15], v[84:85], v[14:15], v[66:67]
	v_mov_b32_e32 v84, v70
	v_cvt_pk_bf16_f32 v14, v14, v15
	v_cvt_pk_bf16_f32 v15, v16, v17
	global_store_dwordx2 v[54:55], v[14:15], off nt
	v_mov_b32_e32 v85, v72
	v_mov_b32_e32 v72, v71
	v_lshlrev_b32_e32 v16, 16, v86
	v_and_b32_e32 v17, 0xffff0000, v86
	v_lshlrev_b32_e32 v82, 16, v87
	v_and_b32_e32 v83, 0xffff0000, v87
	v_pk_mul_f32 v[70:71], v[76:77], v[84:85] op_sel_hi:[0,1]
	v_pk_mul_f32 v[72:73], v[76:77], v[72:73] op_sel_hi:[0,1]
	s_nop 0
	v_mov_b32_e32 v66, v144
	v_mov_b32_e32 v67, v145
	v_mov_b32_e32 v68, v146
	v_mov_b32_e32 v69, v147
	v_pk_fma_f32 v[68:69], v[72:73], v[68:69], v[82:83]
	v_pk_fma_f32 v[16:17], v[70:71], v[66:67], v[16:17]
	v_lshlrev_b32_e32 v70, 16, v20
	v_cvt_pk_bf16_f32 v16, v16, v17
	v_cvt_pk_bf16_f32 v17, v68, v69
	global_store_dwordx2 v[54:55], v[16:17], off offset:512 nt
	v_and_b32_e32 v71, 0xffff0000, v20
	v_lshlrev_b32_e32 v20, 16, v21
	v_and_b32_e32 v21, 0xffff0000, v21
	v_pk_mul_f32 v[72:73], v[76:77], v[74:75] op_sel_hi:[0,1]
	v_pk_mul_f32 v[74:75], v[76:77], v[88:89] op_sel_hi:[0,1]
	v_pk_mul_f32 v[76:77], v[76:77], v[80:81] op_sel_hi:[0,1]
	v_lshlrev_b32_e32 v82, 16, v58
	v_and_b32_e32 v83, 0xffff0000, v58
	v_lshlrev_b32_e32 v58, 16, v59
	v_and_b32_e32 v59, 0xffff0000, v59
	s_nop 0
	v_mov_b32_e32 v66, v148
	v_mov_b32_e32 v67, v149
	v_mov_b32_e32 v68, v150
	v_mov_b32_e32 v69, v151
	v_pk_fma_f32 v[68:69], v[74:75], v[68:69], v[20:21]
	v_pk_fma_f32 v[20:21], v[72:73], v[66:67], v[70:71]
	v_lshlrev_b32_e32 v70, 16, v28
	v_cvt_pk_bf16_f32 v20, v20, v21
	v_cvt_pk_bf16_f32 v21, v68, v69
	global_store_dwordx2 v[54:55], v[20:21], off offset:1024 nt
	v_and_b32_e32 v71, 0xffff0000, v28
	v_lshlrev_b32_e32 v28, 16, v29
	v_and_b32_e32 v29, 0xffff0000, v29
	v_lshlrev_b32_e32 v73, 16, v60
	v_mul_f32_e32 v72, v83, v83
	v_pk_fma_f32 v[86:87], v[82:83], v[82:83], v[72:73] op_sel_hi:[1,1,0]
	v_and_b32_e32 v75, 0xffff0000, v60
	v_lshlrev_b32_e32 v60, 16, v61
	v_and_b32_e32 v61, 0xffff0000, v61
	v_mov_b32_e32 v72, v86
	v_mul_f32_e32 v5, v75, v75
	v_mul_f32_e32 v65, v60, v60
	v_mul_f32_e32 v90, v61, v61
	s_nop 0
	v_mov_b32_e32 v66, v152
	v_mov_b32_e32 v67, v153
	v_mov_b32_e32 v68, v154
	v_mov_b32_e32 v69, v155
	v_pk_fma_f32 v[68:69], v[76:77], v[68:69], v[28:29]
	v_pk_fma_f32 v[28:29], v[78:79], v[66:67], v[70:71]
	v_lshlrev_b32_e32 v71, 16, v63
	v_cvt_pk_bf16_f32 v28, v28, v29
	v_cvt_pk_bf16_f32 v29, v68, v69
	global_store_dwordx2 v[54:55], v[28:29], off offset:1536 nt
	v_lshlrev_b32_e32 v70, 16, v62
	v_and_b32_e32 v63, 0xffff0000, v63
	v_and_b32_e32 v62, 0xffff0000, v62
	v_mul_f32_e32 v54, v59, v59
	v_mov_b32_e32 v55, v73
	v_lshlrev_b32_e32 v76, 16, v56
	v_and_b32_e32 v77, 0xffff0000, v56
	v_lshlrev_b32_e32 v78, 16, v57
	v_and_b32_e32 v79, 0xffff0000, v57
	v_pk_mul_f32 v[56:57], v[62:63], v[62:63]
	v_pk_fma_f32 v[84:85], v[58:59], v[58:59], v[54:55] op_sel_hi:[1,1,0]
	v_mul_f32_e32 v74, v77, v77
	v_mul_f32_e32 v80, v79, v79
	v_pk_fma_f32 v[56:57], v[70:71], v[70:71], v[56:57]
	v_mov_b32_e32 v54, v84
	v_pk_fma_f32 v[88:89], v[76:77], v[76:77], v[74:75] op_sel_hi:[1,1,0]
	v_pk_fma_f32 v[80:81], v[78:79], v[78:79], v[80:81] op_sel_hi:[1,1,0]
	v_pk_add_f32 v[84:85], v[86:87], v[84:85]
	v_pk_add_f32 v[56:57], v[56:57], v[56:57] op_sel:[0,1] op_sel_hi:[1,0]
	v_pk_mul_f32 v[54:55], v[72:73], v[54:55]
	v_mov_b32_e32 v89, v65
	v_mov_b32_e32 v81, v90
	v_mov_b32_e32 v57, v5
	v_mov_b32_e32 v85, v55
	v_pk_add_f32 v[80:81], v[88:89], v[80:81]
	v_pk_add_f32 v[54:55], v[84:85], v[56:57]
	v_mov_b32_e32 v74, v73
	v_pk_add_f32 v[54:55], v[54:55], v[80:81]
	s_nop 0
	v_add_f32_e32 v5, v54, v55
	ds_bpermute_b32 v54, v206, v5
	s_waitcnt lgkmcnt(0)
	v_add_f32_e32 v5, v5, v54
	ds_bpermute_b32 v54, v207, v5
	s_waitcnt lgkmcnt(0)
	v_add_f32_e32 v5, v5, v54
	ds_bpermute_b32 v54, v208, v5
	s_waitcnt lgkmcnt(0)
	v_add_f32_e32 v5, v5, v54
	ds_bpermute_b32 v54, v209, v5
	s_waitcnt lgkmcnt(0)
	v_add_f32_e32 v5, v5, v54
	ds_bpermute_b32 v54, v210, v5
	s_waitcnt lgkmcnt(0)
	v_add_f32_e32 v5, v5, v54
	ds_bpermute_b32 v55, v211, v5
	v_lshlrev_b32_e32 v54, 16, v24
	s_waitcnt lgkmcnt(0)
; DI unsigned cvt_pk_bf16(float lo, float hi) { const f32x2 v = {lo, hi}; return __builtin_bit_cast(unsigned, __builtin_convertvector(v, bf16x2_t)); }
; DI float bflo(unsigned w) { return __uint_as_float(w << 16); }
; DI float bfhi(unsigned w) { return __uint_as_float(w & 0xffff0000u); }
; template <bool XOUT_BF, int NR>
; DI void norm_rows(const bf16_t* xin, const bf16_t* Rb, const float* gpost, void* xout, const float* gpre, bf16_t* xnb, size_t row0, size_t rstride, int lane) {
;     ...
;     for (int q = 0; q < NR; ++q) { const float rinv = __builtin_amdgcn_rsqf(ss[q] * (1.f / 1024.f) + EPS);
; #pragma unroll
;         for (int j = 0; j < 4; ++j) { const size_t off = (row0 + q * rstride) * D + 4 * lane + 256 * j;
;             const f32x4 g = *(const f32x4*)(gpost + 4 * lane + 256 * j); v[q][j] += r[q][j] * rinv * g;
;             if (XOUT_BF) { u32x2 w; w.x = cvt_pk_bf16(v[q][j][0], v[q][j][1]); w.y = cvt_pk_bf16(v[q][j][2], v[q][j][3]); __builtin_nontemporal_store(w, (u32x2*)((bf16_t*)xout + off));
;                            v[q][j] = (f32x4){bflo(w.x), bfhi(w.x), bflo(w.y), bfhi(w.y)}; }
;             else *(f32x4*)((float*)xout + off) = v[q][j];
;             s2[q] += (v[q][j][0] * v[q][j][0] + v[q][j][1] * v[q][j][1]) + (v[q][j][2] * v[q][j][2] + v[q][j][3] * v[q][j][3]); } }
;     if (xnb) {
; #pragma unroll
;         for (int o = 1; o < 64; o <<= 1)
; #pragma unroll
;             for (int q = 0; q < NR; ++q) s2[q] += __shfl_xor(s2[q], o);
	v_add_f32_e32 v5, v5, v55
	v_fmamk_f32 v5, v5, 0x3a800000, v217
	v_rsq_f32_e32 v72, v5
	v_and_b32_e32 v55, 0xffff0000, v24
	v_lshlrev_b32_e32 v24, 16, v25
	v_and_b32_e32 v25, 0xffff0000, v25
	v_pk_mul_f32 v[56:57], v[72:73], v[82:83] op_sel_hi:[0,1]
	v_pk_mul_f32 v[58:59], v[72:73], v[58:59] op_sel_hi:[0,1]
	v_pk_mul_f32 v[60:61], v[72:73], v[60:61] op_sel_hi:[0,1]
	s_nop 0
	v_mov_b32_e32 v66, v140
	v_mov_b32_e32 v67, v141
	v_mov_b32_e32 v68, v142
	v_mov_b32_e32 v69, v143
	v_pk_fma_f32 v[58:59], v[58:59], v[68:69], v[24:25]
	v_pk_fma_f32 v[24:25], v[56:57], v[66:67], v[54:55]
	v_mov_b32_e32 v66, v70
	v_cvt_pk_bf16_f32 v24, v24, v25
	v_cvt_pk_bf16_f32 v25, v58, v59
	global_store_dwordx2 v[34:35], v[24:25], off nt
	v_mov_b32_e32 v67, v62
	v_mov_b32_e32 v62, v71
	v_lshlrev_b32_e32 v58, 16, v26
	v_and_b32_e32 v59, 0xffff0000, v26
	v_lshlrev_b32_e32 v26, 16, v27
	v_and_b32_e32 v27, 0xffff0000, v27
	v_pk_mul_f32 v[66:67], v[72:73], v[66:67] op_sel_hi:[0,1]
	v_pk_mul_f32 v[62:63], v[72:73], v[62:63] op_sel_hi:[0,1]
	v_lshlrev_b32_e32 v68, 16, v37
	v_and_b32_e32 v69, 0xffff0000, v37
	v_lshlrev_b32_e32 v70, 16, v46
	v_and_b32_e32 v71, 0xffff0000, v46
	v_lshlrev_b32_e32 v46, 16, v47
	v_and_b32_e32 v47, 0xffff0000, v47
	v_mul_f32_e32 v65, v68, v68
	v_mul_f32_e32 v80, v69, v69
	s_nop 0
	v_mov_b32_e32 v54, v144
	v_mov_b32_e32 v55, v145
	v_mov_b32_e32 v56, v146
	v_mov_b32_e32 v57, v147
	v_pk_fma_f32 v[56:57], v[62:63], v[56:57], v[26:27]
	v_pk_fma_f32 v[26:27], v[66:67], v[54:55], v[58:59]
	v_lshlrev_b32_e32 v58, 16, v30
	v_cvt_pk_bf16_f32 v26, v26, v27
	v_cvt_pk_bf16_f32 v27, v56, v57
	global_store_dwordx2 v[34:35], v[26:27], off offset:512 nt
	v_and_b32_e32 v59, 0xffff0000, v30
	v_lshlrev_b32_e32 v30, 16, v31
	v_and_b32_e32 v31, 0xffff0000, v31
	v_pk_mul_f32 v[62:63], v[72:73], v[76:77] op_sel_hi:[0,1]
	v_pk_mul_f32 v[66:67], v[72:73], v[78:79] op_sel_hi:[0,1]
	s_nop 0
	v_mov_b32_e32 v54, v148
	v_mov_b32_e32 v55, v149
	v_mov_b32_e32 v56, v150
	v_mov_b32_e32 v57, v151
	v_pk_fma_f32 v[56:57], v[66:67], v[56:57], v[30:31]
	v_pk_fma_f32 v[30:31], v[62:63], v[54:55], v[58:59]
	v_lshlrev_b32_e32 v58, 16, v52
	v_cvt_pk_bf16_f32 v30, v30, v31
	v_cvt_pk_bf16_f32 v31, v56, v57
	global_store_dwordx2 v[34:35], v[30:31], off offset:1024 nt
	v_and_b32_e32 v59, 0xffff0000, v52
	v_lshlrev_b32_e32 v52, 16, v53
	v_and_b32_e32 v53, 0xffff0000, v53
	v_lshlrev_b32_e32 v63, 16, v36
	v_and_b32_e32 v67, 0xffff0000, v36
	v_pk_mul_f32 v[36:37], v[72:73], v[74:75] op_sel_hi:[0,1]
	v_mul_f32_e32 v62, v71, v71
	v_pk_fma_f32 v[76:77], v[70:71], v[70:71], v[62:63] op_sel_hi:[1,1,0]
	v_mul_f32_e32 v5, v67, v67
	v_mov_b32_e32 v62, v76
	s_nop 0
	v_mov_b32_e32 v54, v152
	v_mov_b32_e32 v55, v153
	v_mov_b32_e32 v56, v154
	v_mov_b32_e32 v57, v155
	v_pk_fma_f32 v[52:53], v[60:61], v[56:57], v[52:53]
	v_pk_fma_f32 v[36:37], v[36:37], v[54:55], v[58:59]
	v_lshlrev_b32_e32 v56, 16, v48
	v_cvt_pk_bf16_f32 v36, v36, v37
	v_cvt_pk_bf16_f32 v37, v52, v53
	global_store_dwordx2 v[34:35], v[36:37], off offset:1536 nt
	v_lshlrev_b32_e32 v35, 16, v51
	v_lshlrev_b32_e32 v34, 16, v50
	v_and_b32_e32 v51, 0xffff0000, v51
	v_and_b32_e32 v50, 0xffff0000, v50
	v_and_b32_e32 v57, 0xffff0000, v48
	v_lshlrev_b32_e32 v58, 16, v49
	v_and_b32_e32 v59, 0xffff0000, v49
	v_mul_f32_e32 v48, v47, v47
	v_mov_b32_e32 v49, v63
	v_pk_mul_f32 v[60:61], v[50:51], v[50:51]
	v_pk_fma_f32 v[74:75], v[46:47], v[46:47], v[48:49] op_sel_hi:[1,1,0]
	v_mul_f32_e32 v66, v57, v57
	v_mul_f32_e32 v72, v59, v59
	v_pk_fma_f32 v[60:61], v[34:35], v[34:35], v[60:61]
	v_mov_b32_e32 v48, v74
	v_pk_fma_f32 v[78:79], v[56:57], v[56:57], v[66:67] op_sel_hi:[1,1,0]
	v_pk_fma_f32 v[72:73], v[58:59], v[58:59], v[72:73] op_sel_hi:[1,1,0]
	v_pk_add_f32 v[74:75], v[76:77], v[74:75]
	v_pk_add_f32 v[60:61], v[60:61], v[60:61] op_sel:[0,1] op_sel_hi:[1,0]
	v_pk_mul_f32 v[48:49], v[62:63], v[48:49]
	v_mov_b32_e32 v79, v65
	v_mov_b32_e32 v73, v80
	v_mov_b32_e32 v61, v5
	v_mov_b32_e32 v75, v49
	v_pk_add_f32 v[72:73], v[78:79], v[72:73]
	v_pk_add_f32 v[48:49], v[74:75], v[60:61]
	v_mov_b32_e32 v66, v63
	v_pk_add_f32 v[48:49], v[48:49], v[72:73]
	s_nop 0
	v_add_f32_e32 v5, v48, v49
	ds_bpermute_b32 v48, v206, v5
	s_waitcnt lgkmcnt(0)
	v_add_f32_e32 v5, v5, v48
	ds_bpermute_b32 v48, v207, v5
	s_waitcnt lgkmcnt(0)
	v_add_f32_e32 v5, v5, v48
	ds_bpermute_b32 v48, v208, v5
	s_waitcnt lgkmcnt(0)
	v_add_f32_e32 v5, v5, v48
	ds_bpermute_b32 v48, v209, v5
	s_waitcnt lgkmcnt(0)
	v_add_f32_e32 v5, v5, v48
	ds_bpermute_b32 v48, v210, v5
	s_waitcnt lgkmcnt(0)
	v_add_f32_e32 v5, v5, v48
	ds_bpermute_b32 v49, v211, v5
	v_lshlrev_b32_e32 v48, 16, v32
	s_waitcnt lgkmcnt(0)
; DI unsigned cvt_pk_bf16(float lo, float hi) { const f32x2 v = {lo, hi}; return __builtin_bit_cast(unsigned, __builtin_convertvector(v, bf16x2_t)); }
; DI float bflo(unsigned w) { return __uint_as_float(w << 16); }
; DI float bfhi(unsigned w) { return __uint_as_float(w & 0xffff0000u); }
; template <bool XOUT_BF, int NR>
; DI void norm_rows(const bf16_t* xin, const bf16_t* Rb, const float* gpost, void* xout, const float* gpre, bf16_t* xnb, size_t row0, size_t rstride, int lane) {
;     ...
;     for (int q = 0; q < NR; ++q) { const float rinv = __builtin_amdgcn_rsqf(ss[q] * (1.f / 1024.f) + EPS);
; #pragma unroll
;         for (int j = 0; j < 4; ++j) { const size_t off = (row0 + q * rstride) * D + 4 * lane + 256 * j;
;             const f32x4 g = *(const f32x4*)(gpost + 4 * lane + 256 * j); v[q][j] += r[q][j] * rinv * g;
;             if (XOUT_BF) { u32x2 w; w.x = cvt_pk_bf16(v[q][j][0], v[q][j][1]); w.y = cvt_pk_bf16(v[q][j][2], v[q][j][3]); __builtin_nontemporal_store(w, (u32x2*)((bf16_t*)xout + off));
;                            v[q][j] = (f32x4){bflo(w.x), bfhi(w.x), bflo(w.y), bfhi(w.y)}; }
;             else *(f32x4*)((float*)xout + off) = v[q][j];
;             s2[q] += (v[q][j][0] * v[q][j][0] + v[q][j][1] * v[q][j][1]) + (v[q][j][2] * v[q][j][2] + v[q][j][3] * v[q][j][3]); } }
;     if (xnb) {
; #pragma unroll
;         for (int o = 1; o < 64; o <<= 1)
; #pragma unroll
;             for (int q = 0; q < NR; ++q) s2[q] += __shfl_xor(s2[q], o);
; #pragma unroll
;         for (int q = 0; q < NR; ++q) { const float rinv = __builtin_amdgcn_rsqf(s2[q] * (1.f / 1024.f) + EPS);
; #pragma unroll
;             for (int j = 0; j < 4; ++j) { const size_t off = (row0 + q * rstride) * D + 4 * lane + 256 * j;
;                 const f32x4 g = *(const f32x4*)(gpre + 4 * lane + 256 * j); const f32x4 o = v[q][j] * rinv * g;
;                 u32x2 w; w.x = cvt_pk_bf16(o[0], o[1]); w.y = cvt_pk_bf16(o[2], o[3]); *(u32x2*)(xnb + off) = w; } }
	v_add_f32_e32 v5, v5, v49
	v_fmamk_f32 v5, v5, 0x3a800000, v217
	v_rsq_f32_e32 v60, v5
	v_and_b32_e32 v49, 0xffff0000, v32
	v_lshlrev_b32_e32 v32, 16, v33
	v_and_b32_e32 v33, 0xffff0000, v33
	v_pk_mul_f32 v[70:71], v[60:61], v[70:71] op_sel_hi:[0,1]
	v_pk_mul_f32 v[46:47], v[60:61], v[46:47] op_sel_hi:[0,1]
	s_nop 0
	v_mov_b32_e32 v52, v140
	v_mov_b32_e32 v53, v141
	v_mov_b32_e32 v54, v142
	v_mov_b32_e32 v55, v143
	v_pk_fma_f32 v[46:47], v[46:47], v[54:55], v[32:33]
	v_pk_fma_f32 v[32:33], v[70:71], v[52:53], v[48:49]
	v_mov_b32_e32 v54, v34
	v_cvt_pk_bf16_f32 v32, v32, v33
	v_cvt_pk_bf16_f32 v33, v46, v47
	global_store_dwordx2 v[42:43], v[32:33], off nt
	v_mov_b32_e32 v55, v50
	v_mov_b32_e32 v50, v35
	v_lshlrev_b32_e32 v52, 16, v44
	v_and_b32_e32 v53, 0xffff0000, v44
	v_lshlrev_b32_e32 v44, 16, v45
	v_and_b32_e32 v45, 0xffff0000, v45
	v_pk_mul_f32 v[34:35], v[60:61], v[54:55] op_sel_hi:[0,1]
	v_pk_mul_f32 v[50:51], v[60:61], v[50:51] op_sel_hi:[0,1]
	s_nop 0
	v_mov_b32_e32 v46, v144
	v_mov_b32_e32 v47, v145
	v_mov_b32_e32 v48, v146
	v_mov_b32_e32 v49, v147
	v_pk_fma_f32 v[44:45], v[50:51], v[48:49], v[44:45]
	v_pk_fma_f32 v[34:35], v[34:35], v[46:47], v[52:53]
	v_lshlrev_b32_e32 v48, 16, v38
	v_cvt_pk_bf16_f32 v34, v34, v35
	v_cvt_pk_bf16_f32 v35, v44, v45
	global_store_dwordx2 v[42:43], v[34:35], off offset:512 nt
	v_and_b32_e32 v49, 0xffff0000, v38
	v_lshlrev_b32_e32 v38, 16, v39
	v_and_b32_e32 v39, 0xffff0000, v39
	v_pk_mul_f32 v[50:51], v[60:61], v[56:57] op_sel_hi:[0,1]
	v_pk_mul_f32 v[52:53], v[60:61], v[58:59] op_sel_hi:[0,1]
	s_nop 0
	v_mov_b32_e32 v44, v148
	v_mov_b32_e32 v45, v149
	v_mov_b32_e32 v46, v150
	v_mov_b32_e32 v47, v151
	v_pk_fma_f32 v[46:47], v[52:53], v[46:47], v[38:39]
	v_pk_fma_f32 v[38:39], v[50:51], v[44:45], v[48:49]
	v_lshlrev_b32_e32 v48, 16, v40
	v_cvt_pk_bf16_f32 v38, v38, v39
	v_cvt_pk_bf16_f32 v39, v46, v47
	global_store_dwordx2 v[42:43], v[38:39], off offset:1024 nt
	v_and_b32_e32 v49, 0xffff0000, v40
	v_lshlrev_b32_e32 v40, 16, v41
	v_and_b32_e32 v41, 0xffff0000, v41
	v_pk_mul_f32 v[50:51], v[60:61], v[66:67] op_sel_hi:[0,1]
	v_pk_mul_f32 v[52:53], v[60:61], v[68:69] op_sel_hi:[0,1]
	s_nop 0
	v_mov_b32_e32 v44, v152
	v_mov_b32_e32 v45, v153
	v_mov_b32_e32 v46, v154
	v_mov_b32_e32 v47, v155
	v_pk_fma_f32 v[46:47], v[52:53], v[46:47], v[40:41]
	v_pk_fma_f32 v[40:41], v[50:51], v[44:45], v[48:49]
	s_nop 0
	v_cvt_pk_bf16_f32 v40, v40, v41
	v_cvt_pk_bf16_f32 v41, v46, v47
	global_store_dwordx2 v[42:43], v[40:41], off offset:1536 nt
	s_cbranch_vccnz .LBB0_986
	v_lshlrev_b32_e32 v47, 16, v23
	v_lshlrev_b32_e32 v46, 16, v22
	v_and_b32_e32 v23, 0xffff0000, v23
	v_and_b32_e32 v22, 0xffff0000, v22
	v_and_b32_e32 v53, 0xffff0000, v1
	v_and_b32_e32 v52, 0xffff0000, v0
	v_lshlrev_b32_e32 v54, 16, v2
	v_and_b32_e32 v55, 0xffff0000, v2
	v_lshlrev_b32_e32 v57, 16, v18
	v_pk_mul_f32 v[48:49], v[22:23], v[22:23]
	v_lshlrev_b32_e32 v51, 16, v1
	v_lshlrev_b32_e32 v50, 16, v0
	v_pk_mul_f32 v[0:1], v[52:53], v[52:53]
	v_mul_f32_e32 v56, v54, v54
	v_mul_f32_e32 v2, v55, v55
	v_lshlrev_b32_e32 v58, 16, v3
	v_and_b32_e32 v59, 0xffff0000, v3
	v_mov_b32_e32 v3, v57
	v_pk_fma_f32 v[48:49], v[46:47], v[46:47], v[48:49]
	v_pk_fma_f32 v[0:1], v[50:51], v[50:51], v[0:1]
	v_and_b32_e32 v61, 0xffff0000, v18
	v_lshlrev_b32_e32 v18, 16, v19
	v_and_b32_e32 v19, 0xffff0000, v19
	v_pk_add_f32 v[2:3], v[56:57], v[2:3]
	v_pk_mul_f32 v[62:63], v[56:57], v[56:57]
	v_mul_f32_e32 v56, v59, v59
	v_mul_f32_e32 v5, v61, v61
	v_mul_f32_e32 v60, v18, v18
	v_mul_f32_e32 v65, v19, v19
	v_mov_b32_e32 v3, v63
	v_pk_fma_f32 v[62:63], v[58:59], v[58:59], v[56:57] op_sel_hi:[1,1,0]
	v_pk_add_f32 v[48:49], v[48:49], v[48:49] op_sel:[0,1] op_sel_hi:[1,0]
	v_pk_add_f32 v[0:1], v[0:1], v[0:1] op_sel:[0,1] op_sel_hi:[1,0]
	v_mov_b32_e32 v63, v5
	v_mov_b32_e32 v49, v60
	v_mov_b32_e32 v1, v65
	v_pk_add_f32 v[2:3], v[2:3], v[62:63]
	v_pk_add_f32 v[0:1], v[48:49], v[0:1]
	v_lshl_add_u64 v[48:49], s[60:61], 0, v[10:11]
	v_pk_add_f32 v[0:1], v[2:3], v[0:1]
	v_mov_b32_e32 v60, v57
	v_add_f32_e32 v0, v0, v1
	ds_bpermute_b32 v1, v206, v0
	s_waitcnt lgkmcnt(0)
	v_add_f32_e32 v0, v0, v1
	ds_bpermute_b32 v1, v207, v0
	s_waitcnt lgkmcnt(0)
	v_add_f32_e32 v0, v0, v1
	ds_bpermute_b32 v1, v208, v0
	s_waitcnt lgkmcnt(0)
	v_add_f32_e32 v0, v0, v1
	ds_bpermute_b32 v1, v209, v0
	s_waitcnt lgkmcnt(0)
	v_add_f32_e32 v0, v0, v1
	ds_bpermute_b32 v1, v210, v0
	s_waitcnt lgkmcnt(0)
	v_add_f32_e32 v0, v0, v1
	ds_bpermute_b32 v1, v211, v0
	s_waitcnt lgkmcnt(0)
; DI unsigned cvt_pk_bf16(float lo, float hi) { const f32x2 v = {lo, hi}; return __builtin_bit_cast(unsigned, __builtin_convertvector(v, bf16x2_t)); }
; template <bool XOUT_BF, int NR>
; DI void norm_rows(const bf16_t* xin, const bf16_t* Rb, const float* gpost, void* xout, const float* gpre, bf16_t* xnb, size_t row0, size_t rstride, int lane) {
;     ...
;     if (xnb) {
; #pragma unroll
;         for (int o = 1; o < 64; o <<= 1)
; #pragma unroll
;             for (int q = 0; q < NR; ++q) s2[q] += __shfl_xor(s2[q], o);
; #pragma unroll
;         for (int q = 0; q < NR; ++q) { const float rinv = __builtin_amdgcn_rsqf(s2[q] * (1.f / 1024.f) + EPS);
; #pragma unroll
;             for (int j = 0; j < 4; ++j) { const size_t off = (row0 + q * rstride) * D + 4 * lane + 256 * j;
;                 const f32x4 g = *(const f32x4*)(gpre + 4 * lane + 256 * j); const f32x4 o = v[q][j] * rinv * g;
;                 u32x2 w; w.x = cvt_pk_bf16(o[0], o[1]); w.y = cvt_pk_bf16(o[2], o[3]); *(u32x2*)(xnb + off) = w; } }
	v_add_f32_e32 v0, v0, v1
	v_fmamk_f32 v0, v0, 0x3a800000, v217
	v_rsq_f32_e32 v56, v0
	v_mov_b32_e32 v0, v46
	v_mov_b32_e32 v1, v22
	v_mov_b32_e32 v22, v47
	v_pk_mul_f32 v[0:1], v[56:57], v[0:1] op_sel_hi:[0,1]
	v_pk_mul_f32 v[2:3], v[56:57], v[22:23] op_sel_hi:[0,1]
	s_nop 0
	v_mov_b32_e32 v42, v156
	v_mov_b32_e32 v43, v157
	v_mov_b32_e32 v44, v158
	v_mov_b32_e32 v45, v159
	v_pk_mul_f32 v[2:3], v[44:45], v[2:3]
	v_pk_mul_f32 v[0:1], v[42:43], v[0:1]
	v_mov_b32_e32 v22, v50
	v_cvt_pk_bf16_f32 v0, v0, v1
	v_cvt_pk_bf16_f32 v1, v2, v3
	global_store_dwordx2 v[48:49], v[0:1], off
	v_mov_b32_e32 v23, v52
	v_mov_b32_e32 v52, v51
	v_pk_mul_f32 v[22:23], v[56:57], v[22:23] op_sel_hi:[0,1]
	v_pk_mul_f32 v[42:43], v[56:57], v[52:53] op_sel_hi:[0,1]
	v_pk_mul_f32 v[44:45], v[60:61], v[56:57] op_sel_hi:[1,0]
	v_pk_mul_f32 v[18:19], v[18:19], v[56:57] op_sel_hi:[1,0]
	v_and_b32_e32 v47, 0xffff0000, v28
	v_mul_f32_e32 v5, v47, v47
	s_nop 0
	v_mov_b32_e32 v0, v160
	v_mov_b32_e32 v1, v161
	v_mov_b32_e32 v2, v162
	v_mov_b32_e32 v3, v163
	v_pk_mul_f32 v[2:3], v[2:3], v[42:43]
	v_pk_mul_f32 v[0:1], v[0:1], v[22:23]
	v_pk_mul_f32 v[22:23], v[54:55], v[56:57] op_sel_hi:[1,0]
	v_cvt_pk_bf16_f32 v0, v0, v1
	v_cvt_pk_bf16_f32 v1, v2, v3
	global_store_dwordx2 v[48:49], v[0:1], off offset:512
	v_pk_mul_f32 v[42:43], v[58:59], v[56:57] op_sel_hi:[1,0]
	s_nop 0
	v_mov_b32_e32 v0, v164
	v_mov_b32_e32 v1, v165
	v_mov_b32_e32 v2, v166
	v_mov_b32_e32 v3, v167
	v_pk_mul_f32 v[0:1], v[0:1], v[22:23]
	v_pk_mul_f32 v[2:3], v[2:3], v[42:43]
	v_cvt_pk_bf16_f32 v0, v0, v1
	v_cvt_pk_bf16_f32 v1, v2, v3
	global_store_dwordx2 v[48:49], v[0:1], off offset:1024
	v_lshlrev_b32_e32 v22, 16, v14
	v_and_b32_e32 v23, 0xffff0000, v14
	v_lshlrev_b32_e32 v14, 16, v15
	v_and_b32_e32 v15, 0xffff0000, v15
	v_lshlrev_b32_e32 v43, 16, v17
	v_lshlrev_b32_e32 v42, 16, v16
	v_and_b32_e32 v17, 0xffff0000, v17
	v_and_b32_e32 v16, 0xffff0000, v16
	v_mul_f32_e32 v46, v23, v23
	v_pk_fma_f32 v[56:57], v[22:23], v[22:23], v[46:47] op_sel_hi:[1,1,0]
	s_nop 0
	v_mov_b32_e32 v0, v168
	v_mov_b32_e32 v1, v169
	v_mov_b32_e32 v2, v170
	v_mov_b32_e32 v3, v171
	v_pk_mul_f32 v[2:3], v[18:19], v[2:3]
	v_pk_mul_f32 v[0:1], v[44:45], v[0:1]
	v_and_b32_e32 v19, 0xffff0000, v20
	v_cvt_pk_bf16_f32 v0, v0, v1
	v_cvt_pk_bf16_f32 v1, v2, v3
	global_store_dwordx2 v[48:49], v[0:1], off offset:1536
	v_lshlrev_b32_e32 v45, 16, v28
	v_mul_f32_e32 v44, v15, v15
	v_lshlrev_b32_e32 v18, 16, v20
	v_lshlrev_b32_e32 v20, 16, v21
	v_and_b32_e32 v21, 0xffff0000, v21
	v_pk_mul_f32 v[48:49], v[16:17], v[16:17]
	v_mov_b32_e32 v51, v45
	v_mul_f32_e32 v50, v19, v19
	v_pk_fma_f32 v[54:55], v[14:15], v[14:15], v[44:45] op_sel_hi:[1,1,0]
	v_lshlrev_b32_e32 v28, 16, v29
	v_and_b32_e32 v29, 0xffff0000, v29
	v_mul_f32_e32 v52, v21, v21
	v_pk_fma_f32 v[48:49], v[42:43], v[42:43], v[48:49]
	v_pk_fma_f32 v[58:59], v[18:19], v[18:19], v[50:51] op_sel_hi:[1,1,0]
	v_mov_b32_e32 v44, v56
	v_mov_b32_e32 v50, v54
	v_mul_f32_e32 v60, v28, v28
	v_mul_f32_e32 v61, v29, v29
	v_pk_fma_f32 v[52:53], v[20:21], v[20:21], v[52:53] op_sel_hi:[1,1,0]
	v_pk_add_f32 v[54:55], v[56:57], v[54:55]
	v_pk_add_f32 v[48:49], v[48:49], v[48:49] op_sel:[0,1] op_sel_hi:[1,0]
	v_pk_mul_f32 v[50:51], v[44:45], v[50:51]
	v_mov_b32_e32 v59, v60
	v_mov_b32_e32 v53, v61
	v_mov_b32_e32 v49, v5
	v_mov_b32_e32 v55, v51
	v_pk_add_f32 v[52:53], v[58:59], v[52:53]
	v_pk_add_f32 v[48:49], v[54:55], v[48:49]
	v_mov_b32_e32 v46, v45
	v_pk_add_f32 v[48:49], v[48:49], v[52:53]
	s_nop 0
	v_add_f32_e32 v5, v48, v49
	ds_bpermute_b32 v44, v206, v5
	v_lshl_add_u64 v[48:49], s[58:59], 0, v[176:177]
	s_waitcnt lgkmcnt(0)
	v_add_f32_e32 v5, v5, v44
	ds_bpermute_b32 v44, v207, v5
	s_waitcnt lgkmcnt(0)
	v_add_f32_e32 v5, v5, v44
	ds_bpermute_b32 v44, v208, v5
	s_waitcnt lgkmcnt(0)
	v_add_f32_e32 v5, v5, v44
	ds_bpermute_b32 v44, v209, v5
	s_waitcnt lgkmcnt(0)
	v_add_f32_e32 v5, v5, v44
	ds_bpermute_b32 v44, v210, v5
	s_waitcnt lgkmcnt(0)
	v_add_f32_e32 v5, v5, v44
	ds_bpermute_b32 v44, v211, v5
	s_waitcnt lgkmcnt(0)
	v_add_f32_e32 v5, v5, v44
	v_fmamk_f32 v5, v5, 0x3a800000, v217
	v_rsq_f32_e32 v44, v5
	s_nop 0
	v_pk_mul_f32 v[22:23], v[44:45], v[22:23] op_sel_hi:[0,1]
	v_pk_mul_f32 v[14:15], v[44:45], v[14:15] op_sel_hi:[0,1]
	s_nop 0
	v_mov_b32_e32 v0, v156
	v_mov_b32_e32 v1, v157
	v_mov_b32_e32 v2, v158
	v_mov_b32_e32 v3, v159
	v_pk_mul_f32 v[2:3], v[14:15], v[2:3]
	v_pk_mul_f32 v[0:1], v[22:23], v[0:1]
	v_mov_b32_e32 v14, v42
	v_cvt_pk_bf16_f32 v0, v0, v1
	v_cvt_pk_bf16_f32 v1, v2, v3
	global_store_dwordx2 v[48:49], v[0:1], off
	v_mov_b32_e32 v15, v16
	v_mov_b32_e32 v16, v43
	v_pk_mul_f32 v[14:15], v[44:45], v[14:15] op_sel_hi:[0,1]
	v_pk_mul_f32 v[16:17], v[44:45], v[16:17] op_sel_hi:[0,1]
	v_pk_mul_f32 v[22:23], v[46:47], v[44:45] op_sel_hi:[1,0]
	s_nop 0
	v_mov_b32_e32 v0, v160
	v_mov_b32_e32 v1, v161
	v_mov_b32_e32 v2, v162
	v_mov_b32_e32 v3, v163
	v_pk_mul_f32 v[2:3], v[16:17], v[2:3]
	v_pk_mul_f32 v[0:1], v[14:15], v[0:1]
	v_pk_mul_f32 v[14:15], v[44:45], v[18:19] op_sel_hi:[0,1]
	v_cvt_pk_bf16_f32 v0, v0, v1
	v_cvt_pk_bf16_f32 v1, v2, v3
	global_store_dwordx2 v[48:49], v[0:1], off offset:512
	v_pk_mul_f32 v[16:17], v[44:45], v[20:21] op_sel_hi:[0,1]
	v_lshlrev_b32_e32 v19, 16, v27
	v_lshlrev_b32_e32 v18, 16, v26
	v_and_b32_e32 v21, 0xffff0000, v27
	v_and_b32_e32 v20, 0xffff0000, v26
	v_lshlrev_b32_e32 v27, 16, v36
	v_mov_b32_e32 v43, v27
	s_nop 0
	v_mov_b32_e32 v0, v164
	v_mov_b32_e32 v1, v165
	v_mov_b32_e32 v2, v166
	v_mov_b32_e32 v3, v167
	v_pk_mul_f32 v[2:3], v[16:17], v[2:3]
	v_pk_mul_f32 v[0:1], v[14:15], v[0:1]
	v_lshlrev_b32_e32 v14, 16, v24
	v_cvt_pk_bf16_f32 v0, v0, v1
; DI unsigned cvt_pk_bf16(float lo, float hi) { const f32x2 v = {lo, hi}; return __builtin_bit_cast(unsigned, __builtin_convertvector(v, bf16x2_t)); }
; template <bool XOUT_BF, int NR>
; DI void norm_rows(const bf16_t* xin, const bf16_t* Rb, const float* gpost, void* xout, const float* gpre, bf16_t* xnb, size_t row0, size_t rstride, int lane) {
;     ...
;     if (xnb) {
; #pragma unroll
;         for (int o = 1; o < 64; o <<= 1)
; #pragma unroll
;             for (int q = 0; q < NR; ++q) s2[q] += __shfl_xor(s2[q], o);
; #pragma unroll
;         for (int q = 0; q < NR; ++q) { const float rinv = __builtin_amdgcn_rsqf(s2[q] * (1.f / 1024.f) + EPS);
; #pragma unroll
;             for (int j = 0; j < 4; ++j) { const size_t off = (row0 + q * rstride) * D + 4 * lane + 256 * j;
;                 const f32x4 g = *(const f32x4*)(gpre + 4 * lane + 256 * j); const f32x4 o = v[q][j] * rinv * g;
;                 u32x2 w; w.x = cvt_pk_bf16(o[0], o[1]); w.y = cvt_pk_bf16(o[2], o[3]); *(u32x2*)(xnb + off) = w; } }
	v_cvt_pk_bf16_f32 v1, v2, v3
	global_store_dwordx2 v[48:49], v[0:1], off offset:1024
	v_and_b32_e32 v15, 0xffff0000, v24
	v_lshlrev_b32_e32 v16, 16, v25
	v_and_b32_e32 v17, 0xffff0000, v25
	v_pk_mul_f32 v[24:25], v[28:29], v[44:45] op_sel_hi:[1,0]
	v_and_b32_e32 v29, 0xffff0000, v36
	v_mul_f32_e32 v26, v17, v17
	v_mul_f32_e32 v28, v15, v15
	v_pk_fma_f32 v[46:47], v[16:17], v[16:17], v[26:27] op_sel_hi:[1,1,0]
	v_mul_f32_e32 v5, v29, v29
	s_nop 0
	v_mov_b32_e32 v0, v168
	v_mov_b32_e32 v1, v169
	v_mov_b32_e32 v2, v170
	v_mov_b32_e32 v3, v171
	v_pk_mul_f32 v[2:3], v[24:25], v[2:3]
	v_pk_mul_f32 v[0:1], v[22:23], v[0:1]
	v_and_b32_e32 v23, 0xffff0000, v30
	v_cvt_pk_bf16_f32 v0, v0, v1
	v_cvt_pk_bf16_f32 v1, v2, v3
	global_store_dwordx2 v[48:49], v[0:1], off offset:1536
	v_lshlrev_b32_e32 v22, 16, v30
	v_lshlrev_b32_e32 v24, 16, v31
	v_and_b32_e32 v25, 0xffff0000, v31
	v_lshlrev_b32_e32 v30, 16, v37
	v_and_b32_e32 v31, 0xffff0000, v37
	v_pk_mul_f32 v[36:37], v[20:21], v[20:21]
	v_mul_f32_e32 v42, v23, v23
	v_pk_fma_f32 v[48:49], v[14:15], v[14:15], v[28:29] op_sel_hi:[1,1,0]
	v_mul_f32_e32 v44, v25, v25
	v_pk_fma_f32 v[36:37], v[18:19], v[18:19], v[36:37]
	v_pk_fma_f32 v[50:51], v[22:23], v[22:23], v[42:43] op_sel_hi:[1,1,0]
	v_mov_b32_e32 v26, v48
	v_mov_b32_e32 v42, v46
	v_mul_f32_e32 v52, v30, v30
	v_mul_f32_e32 v53, v31, v31
	v_pk_fma_f32 v[44:45], v[24:25], v[24:25], v[44:45] op_sel_hi:[1,1,0]
	v_pk_add_f32 v[46:47], v[48:49], v[46:47]
	v_pk_add_f32 v[36:37], v[36:37], v[36:37] op_sel:[0,1] op_sel_hi:[1,0]
	v_pk_mul_f32 v[42:43], v[26:27], v[42:43]
	v_mov_b32_e32 v51, v52
	v_mov_b32_e32 v45, v53
	v_mov_b32_e32 v37, v5
	v_mov_b32_e32 v47, v43
	v_pk_add_f32 v[44:45], v[50:51], v[44:45]
	v_pk_add_f32 v[36:37], v[46:47], v[36:37]
	v_mov_b32_e32 v28, v27
	v_pk_add_f32 v[36:37], v[36:37], v[44:45]
	s_nop 0
	v_add_f32_e32 v5, v36, v37
	ds_bpermute_b32 v26, v206, v5
	v_lshl_add_u64 v[36:37], s[48:49], 0, v[176:177]
	s_waitcnt lgkmcnt(0)
	v_add_f32_e32 v5, v5, v26
	ds_bpermute_b32 v26, v207, v5
	s_waitcnt lgkmcnt(0)
	v_add_f32_e32 v5, v5, v26
	ds_bpermute_b32 v26, v208, v5
	s_waitcnt lgkmcnt(0)
	v_add_f32_e32 v5, v5, v26
	ds_bpermute_b32 v26, v209, v5
	s_waitcnt lgkmcnt(0)
	v_add_f32_e32 v5, v5, v26
	ds_bpermute_b32 v26, v210, v5
	s_waitcnt lgkmcnt(0)
	v_add_f32_e32 v5, v5, v26
	ds_bpermute_b32 v26, v211, v5
	s_waitcnt lgkmcnt(0)
; DI unsigned cvt_pk_bf16(float lo, float hi) { const f32x2 v = {lo, hi}; return __builtin_bit_cast(unsigned, __builtin_convertvector(v, bf16x2_t)); }
; template <bool XOUT_BF, int NR>
; DI void norm_rows(const bf16_t* xin, const bf16_t* Rb, const float* gpost, void* xout, const float* gpre, bf16_t* xnb, size_t row0, size_t rstride, int lane) {
;     ...
;     if (xnb) {
; #pragma unroll
;         for (int o = 1; o < 64; o <<= 1)
; #pragma unroll
;             for (int q = 0; q < NR; ++q) s2[q] += __shfl_xor(s2[q], o);
; #pragma unroll
;         for (int q = 0; q < NR; ++q) { const float rinv = __builtin_amdgcn_rsqf(s2[q] * (1.f / 1024.f) + EPS);
; #pragma unroll
;             for (int j = 0; j < 4; ++j) { const size_t off = (row0 + q * rstride) * D + 4 * lane + 256 * j;
;                 const f32x4 g = *(const f32x4*)(gpre + 4 * lane + 256 * j); const f32x4 o = v[q][j] * rinv * g;
;                 u32x2 w; w.x = cvt_pk_bf16(o[0], o[1]); w.y = cvt_pk_bf16(o[2], o[3]); *(u32x2*)(xnb + off) = w; } }
	v_add_f32_e32 v5, v5, v26
	v_fmamk_f32 v5, v5, 0x3a800000, v217
	v_rsq_f32_e32 v26, v5
	s_nop 0
	v_pk_mul_f32 v[14:15], v[26:27], v[14:15] op_sel_hi:[0,1]
	v_pk_mul_f32 v[16:17], v[26:27], v[16:17] op_sel_hi:[0,1]
	s_nop 0
	v_mov_b32_e32 v0, v156
	v_mov_b32_e32 v1, v157
	v_mov_b32_e32 v2, v158
	v_mov_b32_e32 v3, v159
	v_pk_mul_f32 v[2:3], v[16:17], v[2:3]
	v_pk_mul_f32 v[0:1], v[14:15], v[0:1]
	v_mov_b32_e32 v14, v18
	v_cvt_pk_bf16_f32 v0, v0, v1
	v_cvt_pk_bf16_f32 v1, v2, v3
	global_store_dwordx2 v[36:37], v[0:1], off
	v_mov_b32_e32 v15, v20
	v_mov_b32_e32 v20, v19
	v_pk_mul_f32 v[14:15], v[26:27], v[14:15] op_sel_hi:[0,1]
	v_pk_mul_f32 v[16:17], v[26:27], v[20:21] op_sel_hi:[0,1]
	v_and_b32_e32 v21, 0xffff0000, v35
	v_and_b32_e32 v20, 0xffff0000, v34
	v_lshlrev_b32_e32 v19, 16, v35
	v_lshlrev_b32_e32 v18, 16, v34
	s_nop 0
	v_mov_b32_e32 v0, v160
	v_mov_b32_e32 v1, v161
	v_mov_b32_e32 v2, v162
	v_mov_b32_e32 v3, v163
	v_pk_mul_f32 v[2:3], v[16:17], v[2:3]
	v_pk_mul_f32 v[0:1], v[14:15], v[0:1]
	v_pk_mul_f32 v[14:15], v[26:27], v[22:23] op_sel_hi:[0,1]
	v_cvt_pk_bf16_f32 v0, v0, v1
	v_cvt_pk_bf16_f32 v1, v2, v3
	global_store_dwordx2 v[36:37], v[0:1], off offset:512
	v_pk_mul_f32 v[16:17], v[26:27], v[24:25] op_sel_hi:[0,1]
	v_pk_mul_f32 v[22:23], v[28:29], v[26:27] op_sel_hi:[1,0]
	v_pk_mul_f32 v[24:25], v[30:31], v[26:27] op_sel_hi:[1,0]
	v_lshlrev_b32_e32 v27, 16, v40
	v_and_b32_e32 v29, 0xffff0000, v40
	v_lshlrev_b32_e32 v30, 16, v41
	v_and_b32_e32 v31, 0xffff0000, v41
	v_mov_b32_e32 v35, v27
	v_mul_f32_e32 v5, v29, v29
	v_mul_f32_e32 v44, v30, v30
	v_mul_f32_e32 v45, v31, v31
	s_nop 0
	v_mov_b32_e32 v0, v164
	v_mov_b32_e32 v1, v165
	v_mov_b32_e32 v2, v166
	v_mov_b32_e32 v3, v167
	v_pk_mul_f32 v[2:3], v[16:17], v[2:3]
	v_pk_mul_f32 v[0:1], v[14:15], v[0:1]
	v_and_b32_e32 v15, 0xffff0000, v32
	v_cvt_pk_bf16_f32 v0, v0, v1
	v_cvt_pk_bf16_f32 v1, v2, v3
	global_store_dwordx2 v[36:37], v[0:1], off offset:1024
	v_and_b32_e32 v17, 0xffff0000, v33
	v_lshlrev_b32_e32 v14, 16, v32
	v_lshlrev_b32_e32 v16, 16, v33
	v_mul_f32_e32 v26, v17, v17
	v_mul_f32_e32 v28, v15, v15
	v_pk_mul_f32 v[32:33], v[20:21], v[20:21]
	v_pk_fma_f32 v[40:41], v[14:15], v[14:15], v[28:29] op_sel_hi:[1,1,0]
	v_pk_fma_f32 v[32:33], v[18:19], v[18:19], v[32:33]
	v_mov_b32_e32 v28, v27
	v_pk_add_f32 v[32:33], v[32:33], v[32:33] op_sel:[0,1] op_sel_hi:[1,0]
	s_nop 0
	v_mov_b32_e32 v0, v168
	v_mov_b32_e32 v1, v169
	v_mov_b32_e32 v2, v170
	v_mov_b32_e32 v3, v171
	v_pk_mul_f32 v[2:3], v[24:25], v[2:3]
	v_pk_mul_f32 v[0:1], v[22:23], v[0:1]
	v_and_b32_e32 v23, 0xffff0000, v38
	v_cvt_pk_bf16_f32 v0, v0, v1
	v_cvt_pk_bf16_f32 v1, v2, v3
	global_store_dwordx2 v[36:37], v[0:1], off offset:1536
	v_lshlrev_b32_e32 v22, 16, v38
	v_lshlrev_b32_e32 v24, 16, v39
	v_and_b32_e32 v25, 0xffff0000, v39
	v_mul_f32_e32 v34, v23, v23
	v_pk_fma_f32 v[38:39], v[16:17], v[16:17], v[26:27] op_sel_hi:[1,1,0]
	v_mul_f32_e32 v36, v25, v25
	v_pk_fma_f32 v[42:43], v[22:23], v[22:23], v[34:35] op_sel_hi:[1,1,0]
	v_mov_b32_e32 v26, v40
	v_mov_b32_e32 v34, v38
	v_pk_fma_f32 v[36:37], v[24:25], v[24:25], v[36:37] op_sel_hi:[1,1,0]
	v_pk_add_f32 v[38:39], v[40:41], v[38:39]
	v_pk_mul_f32 v[34:35], v[26:27], v[34:35]
	v_mov_b32_e32 v43, v44
	v_mov_b32_e32 v37, v45
	v_mov_b32_e32 v33, v5
	v_mov_b32_e32 v39, v35
	v_pk_add_f32 v[36:37], v[42:43], v[36:37]
	v_pk_add_f32 v[32:33], v[38:39], v[32:33]
	s_nop 0
	v_pk_add_f32 v[32:33], v[32:33], v[36:37]
	s_nop 0
	v_add_f32_e32 v5, v32, v33
	ds_bpermute_b32 v26, v206, v5
	v_lshl_add_u64 v[32:33], s[56:57], 0, v[176:177]
	s_waitcnt lgkmcnt(0)
	v_add_f32_e32 v5, v5, v26
	ds_bpermute_b32 v26, v207, v5
	s_waitcnt lgkmcnt(0)
	v_add_f32_e32 v5, v5, v26
	ds_bpermute_b32 v26, v208, v5
	s_waitcnt lgkmcnt(0)
	v_add_f32_e32 v5, v5, v26
	ds_bpermute_b32 v26, v209, v5
	s_waitcnt lgkmcnt(0)
	v_add_f32_e32 v5, v5, v26
	ds_bpermute_b32 v26, v210, v5
	s_waitcnt lgkmcnt(0)
	v_add_f32_e32 v5, v5, v26
	ds_bpermute_b32 v26, v211, v5
	s_waitcnt lgkmcnt(0)
	v_add_f32_e32 v5, v5, v26
	v_fmamk_f32 v5, v5, 0x3a800000, v217
	v_rsq_f32_e32 v26, v5
	s_nop 0
	v_pk_mul_f32 v[14:15], v[26:27], v[14:15] op_sel_hi:[0,1]
	v_pk_mul_f32 v[16:17], v[26:27], v[16:17] op_sel_hi:[0,1]
	s_nop 0
	v_mov_b32_e32 v0, v156
	v_mov_b32_e32 v1, v157
	v_mov_b32_e32 v2, v158
	v_mov_b32_e32 v3, v159
	v_pk_mul_f32 v[2:3], v[16:17], v[2:3]
	v_pk_mul_f32 v[0:1], v[14:15], v[0:1]
	v_mov_b32_e32 v14, v18
	v_cvt_pk_bf16_f32 v0, v0, v1
	v_cvt_pk_bf16_f32 v1, v2, v3
	global_store_dwordx2 v[32:33], v[0:1], off
	v_mov_b32_e32 v15, v20
	v_mov_b32_e32 v20, v19
	v_pk_mul_f32 v[14:15], v[26:27], v[14:15] op_sel_hi:[0,1]
	v_pk_mul_f32 v[16:17], v[26:27], v[20:21] op_sel_hi:[0,1]
	s_nop 0
	v_mov_b32_e32 v0, v160
	v_mov_b32_e32 v1, v161
	v_mov_b32_e32 v2, v162
	v_mov_b32_e32 v3, v163
	v_pk_mul_f32 v[2:3], v[16:17], v[2:3]
	v_pk_mul_f32 v[0:1], v[14:15], v[0:1]
	v_pk_mul_f32 v[14:15], v[26:27], v[22:23] op_sel_hi:[0,1]
	v_cvt_pk_bf16_f32 v0, v0, v1
	v_cvt_pk_bf16_f32 v1, v2, v3
	global_store_dwordx2 v[32:33], v[0:1], off offset:512
	v_pk_mul_f32 v[16:17], v[26:27], v[24:25] op_sel_hi:[0,1]
	s_nop 0
	v_mov_b32_e32 v0, v164
	v_mov_b32_e32 v1, v165
	v_mov_b32_e32 v2, v166
	v_mov_b32_e32 v3, v167
	v_pk_mul_f32 v[2:3], v[16:17], v[2:3]
	v_pk_mul_f32 v[0:1], v[14:15], v[0:1]
	v_pk_mul_f32 v[14:15], v[28:29], v[26:27] op_sel_hi:[1,0]
	v_cvt_pk_bf16_f32 v0, v0, v1
	v_cvt_pk_bf16_f32 v1, v2, v3
	global_store_dwordx2 v[32:33], v[0:1], off offset:1024
	v_pk_mul_f32 v[16:17], v[30:31], v[26:27] op_sel_hi:[1,0]
	s_nop 0
	v_mov_b32_e32 v0, v168
	v_mov_b32_e32 v1, v169
	v_mov_b32_e32 v2, v170
	v_mov_b32_e32 v3, v171
	v_pk_mul_f32 v[0:1], v[14:15], v[0:1]
	v_pk_mul_f32 v[2:3], v[16:17], v[2:3]
	v_cvt_pk_bf16_f32 v0, v0, v1
	v_cvt_pk_bf16_f32 v1, v2, v3
	global_store_dwordx2 v[32:33], v[0:1], off offset:1536
	s_branch .LBB0_986
